# att6 plus c=1 waves fetch first V k-step of the lagging PV ahead of the end-of-tile barrier
# speedup vs baseline: 1.0011x; 1.0011x over previous
; #define ATT_WAITBAR(N) asm volatile("s_waitcnt vmcnt(" #N ") lgkmcnt(0)\n\ts_barrier" ::: "memory")
; #define ATT_PV(slot) do { bf16x8 va[4], vb[4]; ATT_LDV(va, slot, 0); ATT_SB; ATT_LDV(vb, slot, 1); ATT_SB; ATT_MMV(va, 0); ATT_SB; ATT_LDV(va, slot, 2); ATT_SB; ATT_MMV(vb, 1); ATT_SB; \
;         ATT_LDV(vb, slot, 3); ATT_SB; ATT_MMV(va, 2); ATT_SB; ATT_MMV(vb, 3); ATT_SB; } while (0)
; template <bool NOSHIFT> __device__ __forceinline__ void diff_attn_unit(LAS unsigned char* lds, bf16_t* proj, const bf16_t* VT, int b, int h, int qb, const AttnConsts ac, const float* gsub, const int tid, bf16_t* obuf, int opitch, int ocol) {
;     ...
;     const int NT = 2 * qb + 2;
;     f32x16 o[4];
; #pragma unroll
;     for (int dt = 0; dt < 4; ++dt)
; #pragma unroll
;         for (int r = 0; r < 16; ++r) o[dt][r] = 0.f;
;     float l = 0.f;
;     bf16x8 pf[4];
; #pragma unroll
;     for (int kk = 0; kk < 4; ++kk) pf[kk] = (bf16x8){0, 0, 0, 0, 0, 0, 0, 0};
;     const int qmax = q0 + 32 * wq + 31;
;     ...
;     ATT_ISSUE(0); ATT_ISSUE(1);
;     ATT_WAITBAR(4);
;     for (int t = 0; t < NT; ++t) {
;         const int bo = (t & 3) * 16384, sl_cur = bo, sl_prev = ((t - 1) & 3) * 16384;
;         if (t + 2 < NT) ATT_ISSUE(t + 2);
;         const int kv0 = 64 * t;
;         if (c == 1 && t >= 1 && kv0 - 64 <= qmax) ATT_PV(sl_prev);
.LBB1_286:
	s_lshl_b32 s45, s84, 1
	s_or_b32 s44, s76, 31
	s_add_i32 s83, s76, 0x5f
	s_cmp_lg_u32 s79, 1
	s_cselect_b64 s[76:77], -1, 0
	s_cmp_eq_u32 s79, 1
	s_cselect_b64 s[74:75], -1, 0
	s_add_i32 s81, s81, s60
	v_add_u32_e32 v2, s81, v116
	v_ashrrev_i32_e32 v3, 31, v2
	v_lshlrev_b64 v[2:3], 15, v[2:3]
	v_and_b32_e32 v0, 7, v117
	v_lshl_add_u64 v[2:3], s[36:37], 0, v[2:3]
	v_lshlrev_b32_e32 v0, 4, v0
	v_lshl_add_u64 v[2:3], v[2:3], 0, v[0:1]
	v_add_u32_e32 v0, s80, v114
	v_mov_b64_e32 v[4:5], s[68:69]
	v_mad_i64_i32 v[4:5], s[14:15], v0, s33, v[4:5]
	v_and_b32_e32 v0, 15, v115
	s_add_i32 s14, s85, s78
	v_lshlrev_b32_e32 v0, 4, v0
	s_sub_i32 s14, s14, 64
	v_lshl_add_u64 v[4:5], v[4:5], 0, v[0:1]
	s_lshl_b32 s57, s84, 15
	v_add_u32_e32 v0, s14, v112
	v_and_b32_e32 v6, 63, v113
	s_mov_b32 s82, 1
	s_bitset1_b32 s57, 14
	s_mov_b32 s47, 64
	v_sub_u32_e32 v0, v0, v182
	s_mov_b32 s14, 0
	s_and_b64 vcc, exec, s[74:75]
	s_cbranch_vccz .Latt_pf0_skip
	ds_read_b128 v[208:211], v193
	ds_read_b128 v[212:215], v193 offset:4096
	ds_read_b128 v[216:219], v193 offset:8192
	ds_read_b128 v[220:223], v193 offset:12288
.Latt_pf0_skip:
	s_cmp_ge_u32 s82, s45
	s_cselect_b64 s[78:79], -1, 0
	s_and_b64 vcc, exec, s[78:79]
	s_cbranch_vccnz .LBB1_288
.LBB1_287:
.LBB1_288:
	s_cmp_gt_u32 s47, s83
	s_cselect_b64 s[80:81], -1, 0
	s_or_b64 s[80:81], s[76:77], s[80:81]
	s_and_b64 vcc, exec, s[80:81]
	s_cbranch_vccnz .LBB1_290
	s_add_i32 s15, s14, 0x10000
	s_and_b32 s15, s15, 0xc000
	v_add_u32_e32 v7, s15, v204
	ds_read_b128 v[120:123], v7
	ds_read_b128 v[124:127], v7 offset:4096
	ds_read_b128 v[128:131], v7 offset:8192
	ds_read_b128 v[132:135], v7 offset:12288
	s_setprio 1
	s_waitcnt lgkmcnt(4)
	v_mfma_f32_32x32x16_bf16 v[80:95], v[208:211], v[104:107], v[80:95]
	v_mfma_f32_32x32x16_bf16 v[64:79], v[212:215], v[104:107], v[64:79]
	v_mfma_f32_32x32x16_bf16 v[48:63], v[216:219], v[104:107], v[48:63]
	v_mfma_f32_32x32x16_bf16 v[32:47], v[220:223], v[104:107], v[32:47]
	s_setprio 0
	v_add_u32_e32 v7, s15, v205
	ds_read_b128 v[8:11], v7
	ds_read_b128 v[12:15], v7 offset:4096
	ds_read_b128 v[112:115], v7 offset:8192
	ds_read_b128 v[116:119], v7 offset:12288
	s_setprio 1
	s_waitcnt lgkmcnt(7)
	v_mfma_f32_32x32x16_bf16 v[80:95], v[120:123], v[100:103], v[80:95]
	s_waitcnt lgkmcnt(6)
	v_mfma_f32_32x32x16_bf16 v[64:79], v[124:127], v[100:103], v[64:79]
	s_waitcnt lgkmcnt(5)
	v_mfma_f32_32x32x16_bf16 v[48:63], v[128:131], v[100:103], v[48:63]
	s_waitcnt lgkmcnt(4)
	v_mfma_f32_32x32x16_bf16 v[32:47], v[132:135], v[100:103], v[32:47]
	s_setprio 0
	v_add_u32_e32 v7, s15, v206
	ds_read_b128 v[120:123], v7
	ds_read_b128 v[124:127], v7 offset:4096
	ds_read_b128 v[128:131], v7 offset:8192
	ds_read_b128 v[132:135], v7 offset:12288
	s_setprio 1
	s_waitcnt lgkmcnt(7)
	v_mfma_f32_32x32x16_bf16 v[80:95], v[8:11], v[96:99], v[80:95]
	s_waitcnt lgkmcnt(6)
	v_mfma_f32_32x32x16_bf16 v[64:79], v[12:15], v[96:99], v[64:79]
	s_waitcnt lgkmcnt(5)
	v_mfma_f32_32x32x16_bf16 v[48:63], v[112:115], v[96:99], v[48:63]
	s_waitcnt lgkmcnt(4)
	v_mfma_f32_32x32x16_bf16 v[32:47], v[116:119], v[96:99], v[32:47]
	s_setprio 0
	s_setprio 1
	s_waitcnt lgkmcnt(3)
	v_mfma_f32_32x32x16_bf16 v[80:95], v[120:123], v[108:111], v[80:95]
	s_waitcnt lgkmcnt(2)
	v_mfma_f32_32x32x16_bf16 v[64:79], v[124:127], v[108:111], v[64:79]
	s_waitcnt lgkmcnt(1)
	v_mfma_f32_32x32x16_bf16 v[48:63], v[128:131], v[108:111], v[48:63]
	s_waitcnt lgkmcnt(0)
	v_mfma_f32_32x32x16_bf16 v[32:47], v[132:135], v[108:111], v[32:47]
	s_setprio 0

; #define ATT_PV(slot) do { bf16x8 va[4], vb[4]; ATT_LDV(va, slot, 0); ATT_SB; ATT_LDV(vb, slot, 1); ATT_SB; ATT_MMV(va, 0); ATT_SB; ATT_LDV(va, slot, 2); ATT_SB; ATT_MMV(vb, 1); ATT_SB; \
;         ATT_LDV(vb, slot, 3); ATT_SB; ATT_MMV(va, 2); ATT_SB; ATT_MMV(vb, 3); ATT_SB; } while (0)
; template <bool NOSHIFT> __device__ __forceinline__ void diff_attn_unit(LAS unsigned char* lds, bf16_t* proj, const bf16_t* VT, int b, int h, int qb, const AttnConsts ac, const float* gsub, const int tid, bf16_t* obuf, int opitch, int ocol) {
;     ...
;         if (c == 1 && t >= 1 && kv0 - 64 <= qmax) ATT_PV(sl_prev);
.Latt_dmadone:
	s_and_b64 vcc, exec, s[74:75]
	s_cbranch_vccz .Latt_pf_skip
	v_add_u32_e32 v8, s15, v193
	ds_read_b128 v[208:211], v8
	ds_read_b128 v[212:215], v8 offset:4096
	ds_read_b128 v[216:219], v8 offset:8192
	ds_read_b128 v[220:223], v8 offset:12288

; __global__ void __launch_bounds__(512, 2) mega(Args args) {
;     ...
;         if (ph + 1 < args.hi) { if (!(args.flags & FL_XCDBAR) || ph == args.lo) grid.sync(); else xcd_barrier(xbar); }
;     }
; }
.Lpost_getpc0:
	s_add_u32 s98, s98, (.LBB1_9-.Lpost_getpc0)&4294967295
	s_addc_u32 s99, s99, (.LBB1_9-.Lpost_getpc0)>>32
	s_setpc_b64 s[98:99]
	s_nop 0
	s_nop 0
	s_nop 0
	s_nop 0
	s_nop 0
	s_nop 0
	s_nop 0
	s_nop 0
	s_nop 0
	s_nop 0
	s_nop 0
	s_nop 0
	s_nop 0
	s_nop 0
	s_nop 0
	s_nop 0
.LBB1_793:
	s_endpgm
